# v90 + prep_run rows: pooling window update (ua-ur sums) and its vmcnt wait deferred from before the rope section to the row latch, so the row's pooling loads overlap the q/k norm+rope compute
# speedup vs baseline: 1.0057x; 1.0057x over previous
.LBB0_452:
	s_or_b64 exec, exec, s[0:1]
	v_sub_u32_e32 v9, v19, v64
	v_cvt_f32_i32_e32 v9, v9
	s_waitcnt vmcnt(2)
	v_lshlrev_b32_e32 v200, 16, v196
	v_and_b32_e32 v201, 0xffff0000, v196
	v_lshlrev_b32_e32 v202, 16, v198
	v_and_b32_e32 v203, 0xffff0000, v198
	v_pk_add_f32 v[200:201], v[200:201], v[202:203] neg_lo:[0,1] neg_hi:[0,1]
	v_lshlrev_b32_e32 v198, 16, v199
	v_pk_add_f32 v[42:43], v[42:43], v[200:201]
	v_lshlrev_b32_e32 v200, 16, v197
	v_and_b32_e32 v201, 0xffff0000, v197
	v_and_b32_e32 v199, 0xffff0000, v199
	v_pk_add_f32 v[200:201], v[200:201], v[198:199] neg_lo:[0,1] neg_hi:[0,1]
	s_nop 0
	v_pk_add_f32 v[40:41], v[40:41], v[200:201]
	v_lshlrev_b32_e32 v38, 16, v36
	v_and_b32_e32 v39, 0xffff0000, v36
	s_add_i32 s14, s14, 1
	v_rcp_iflag_f32_e32 v34, v9
	v_lshlrev_b64 v[26:27], 11, v[26:27]
	v_lshl_add_u64 v[26:27], v[12:13], 0, v[26:27]
	v_add_u32_e32 v63, 1, v63
	v_pk_fma_f32 v[38:39], v[34:35], v[42:43], v[38:39] op_sel_hi:[0,1,1] neg_lo:[0,0,1] neg_hi:[0,0,1]
	v_cvt_pk_bf16_f32 v36, v38, v39
	v_lshlrev_b32_e32 v38, 16, v37
	v_and_b32_e32 v39, 0xffff0000, v37
	v_pk_fma_f32 v[34:35], v[34:35], v[40:41], v[38:39] op_sel_hi:[0,1,1] neg_lo:[0,0,1] neg_hi:[0,0,1]
	v_cvt_pk_bf16_f32 v37, v34, v35
	s_cmp_eq_u32 s14, 10
	v_mov_b32_e32 v23, v19
	v_mov_b32_e32 v46, v28
	v_mov_b32_e32 v47, v29
	v_mov_b32_e32 v44, v30
	v_mov_b32_e32 v45, v31
	v_mov_b32_e32 v38, v32
	v_mov_b32_e32 v39, v33
	global_store_dwordx2 v[26:27], v[36:37], off
	s_cbranch_scc1 .LBB0_475

.LBB0_455:
	s_movk_i32 s0, 0x3fff
	v_cmp_lt_i32_e64 s[40:41], s0, v26
	v_mov_b32_e32 v9, 0x7ff
	s_movk_i32 s0, 0x1200
	v_cndmask_b32_e64 v9, v9, v238, s[40:41]
	v_and_b32_e32 v9, v9, v26
	v_sub_u32_e32 v17, v26, v9
	v_mad_i64_i32 v[48:49], s[0:1], v17, s0, v[10:11]
	v_mul_u32_u24_e32 v17, 0x900, v9
	v_lshlrev_b32_e32 v160, 1, v17
	v_lshl_add_u64 v[36:37], v[48:49], 0, v[160:161]
	global_load_dwordx2 v[36:37], v[36:37], off
	v_mov_b32_e32 v17, 0x800
	s_cmp_lg_u32 s14, 0
	v_cndmask_b32_e64 v19, v17, v245, s[40:41]
	v_add_u32_e32 v21, v9, v58
	s_cselect_b64 s[4:5], -1, 0
	v_cmp_ne_u32_e64 s[0:1], 0, v9
	v_ashrrev_i32_e32 v27, 31, v26
	v_sub_u32_e32 v17, v9, v58
	v_min_u32_e32 v19, v21, v19
	s_and_b64 s[0:1], s[4:5], s[0:1]
	v_mov_b32_e32 v196, 0
	v_mov_b32_e32 v197, 0
	v_mov_b32_e32 v198, 0
	v_mov_b32_e32 v199, 0
	s_and_saveexec_b64 s[4:5], s[0:1]
	s_xor_b64 s[4:5], exec, s[4:5]
	s_cbranch_execz .LBB0_461
	v_cmp_gt_u32_e64 s[0:1], v19, v23
	v_mov_b32_e32 v198, 0
	v_mov_b32_e32 v196, 0
	v_mov_b32_e32 v197, 0
	s_and_saveexec_b64 s[6:7], s[0:1]
	s_cbranch_execz .LBB0_458
	v_add_u32_e32 v21, -1, v19
	s_movk_i32 s0, 0x1200
	v_mad_u64_u32 v[52:53], s[0:1], v21, s0, v[48:49]
	global_load_dwordx2 v[196:197], v[52:53], off
.LBB0_458:
	s_or_b64 exec, exec, s[6:7]
	v_cmp_gt_i32_e64 s[0:1], v17, v64
	v_mov_b32_e32 v199, 0
	s_and_saveexec_b64 s[6:7], s[0:1]
	s_cbranch_execz .LBB0_460
	s_movk_i32 s0, 0x1200
	v_mad_u64_u32 v[48:49], s[0:1], v64, s0, v[48:49]
	global_load_dwordx2 v[198:199], v[48:49], off
.LBB0_460:
	s_or_b64 exec, exec, s[6:7]
.LBB0_461:
	s_or_saveexec_b64 s[4:5], s[4:5]
	v_max_i32_e32 v64, 0, v17
	s_xor_b64 exec, exec, s[4:5]
	s_cbranch_execz .LBB0_473
	v_cmp_lt_i32_e64 s[0:1], v17, v19
	v_mov_b32_e32 v43, 0
	v_mov_b32_e32 v42, 0
	v_mov_b32_e32 v41, 0
	v_mov_b32_e32 v40, 0
	s_and_saveexec_b64 s[6:7], s[0:1]
	s_cbranch_execz .LBB0_472
	v_add_u32_e32 v21, 1, v64
	v_max_u32_e32 v54, v19, v21
	s_movk_i32 s0, 0x1200
	v_sub_u32_e32 v17, v54, v64
	v_mad_i64_i32 v[50:51], s[0:1], v63, s0, 0
	v_and_b32_e32 v23, 3, v17
	v_mov_b32_e32 v160, v161
	v_cmp_ne_u32_e64 s[0:1], 0, v23
	v_mul_hi_u32_u24_e32 v52, 0x1200, v9
	v_mul_u32_u24_e32 v53, 0x1200, v9
	v_add_u32_e32 v25, v64, v23
	v_mov_b64_e32 v[42:43], v[160:161]
	v_mov_b64_e32 v[40:41], v[160:161]
	v_mov_b32_e32 v17, v64
	s_and_saveexec_b64 s[8:9], s[0:1]
	s_cbranch_execz .LBB0_467
	s_movk_i32 s0, 0x1200
	v_mad_u64_u32 v[40:41], s[0:1], v64, s0, v[50:51]
	v_sub_co_u32_e64 v40, s[0:1], v40, v53
	v_mul_u32_u24_e32 v17, 0x1200, v23
	s_nop 0
	v_subb_co_u32_e64 v41, s[0:1], v41, v52, s[0:1]
	v_lshl_add_u64 v[48:49], v[10:11], 0, v[40:41]
	v_mov_b32_e32 v40, 0
	s_mov_b64 s[10:11], 0
	v_mov_b32_e32 v41, v40
	v_mov_b32_e32 v42, v40
	v_mov_b32_e32 v43, v40

.LBB0_477:
	s_or_b64 exec, exec, s[0:1]
	v_sub_u32_e32 v9, v19, v64
	v_cvt_f32_i32_e32 v9, v9
	s_waitcnt vmcnt(2)
	v_lshlrev_b32_e32 v200, 16, v196
	v_and_b32_e32 v201, 0xffff0000, v196
	v_lshlrev_b32_e32 v202, 16, v198
	v_and_b32_e32 v203, 0xffff0000, v198
	v_pk_add_f32 v[200:201], v[200:201], v[202:203] neg_lo:[0,1] neg_hi:[0,1]
	v_lshlrev_b32_e32 v198, 16, v199
	v_pk_add_f32 v[42:43], v[42:43], v[200:201]
	v_lshlrev_b32_e32 v200, 16, v197
	v_and_b32_e32 v201, 0xffff0000, v197
	v_and_b32_e32 v199, 0xffff0000, v199
	v_pk_add_f32 v[200:201], v[200:201], v[198:199] neg_lo:[0,1] neg_hi:[0,1]
	s_nop 0
	v_pk_add_f32 v[40:41], v[40:41], v[200:201]
	v_lshlrev_b32_e32 v38, 16, v36
	v_and_b32_e32 v39, 0xffff0000, v36
	s_add_i32 s10, s10, 1
	v_rcp_iflag_f32_e32 v34, v9
	v_lshlrev_b64 v[26:27], 11, v[26:27]
	v_lshl_add_u64 v[26:27], v[12:13], 0, v[26:27]
	v_add_u32_e32 v63, 1, v63
	v_pk_fma_f32 v[38:39], v[34:35], v[42:43], v[38:39] op_sel_hi:[0,1,1] neg_lo:[0,0,1] neg_hi:[0,0,1]
	v_cvt_pk_bf16_f32 v36, v38, v39
	v_lshlrev_b32_e32 v38, 16, v37
	v_and_b32_e32 v39, 0xffff0000, v37
	v_pk_fma_f32 v[34:35], v[34:35], v[40:41], v[38:39] op_sel_hi:[0,1,1] neg_lo:[0,0,1] neg_hi:[0,0,1]
	v_cvt_pk_bf16_f32 v37, v34, v35
	s_cmp_eq_u32 s10, 11
	v_mov_b32_e32 v23, v19
	v_mov_b32_e32 v46, v28
	v_mov_b32_e32 v47, v29
	v_mov_b32_e32 v44, v30
	v_mov_b32_e32 v45, v31
	v_mov_b32_e32 v38, v32
	v_mov_b32_e32 v39, v33
	global_store_dwordx2 v[26:27], v[36:37], off
	s_cbranch_scc1 .LBB0_500

.LBB0_480:
	s_movk_i32 s0, 0x3fff
	v_cmp_lt_i32_e64 s[40:41], s0, v26
	v_mov_b32_e32 v9, 0x7ff
	s_movk_i32 s0, 0x1200
	v_cndmask_b32_e64 v9, v9, v238, s[40:41]
	v_and_b32_e32 v9, v9, v26
	v_sub_u32_e32 v17, v26, v9
	v_mad_i64_i32 v[48:49], s[0:1], v17, s0, v[10:11]
	v_mul_u32_u24_e32 v17, 0x900, v9
	v_lshlrev_b32_e32 v160, 1, v17
	v_lshl_add_u64 v[36:37], v[48:49], 0, v[160:161]
	global_load_dwordx2 v[36:37], v[36:37], off
	v_mov_b32_e32 v17, 0x800
	s_cmp_lg_u32 s10, 0
	v_cndmask_b32_e64 v19, v17, v245, s[40:41]
	v_add_u32_e32 v21, v9, v58
	s_cselect_b64 s[2:3], -1, 0
	v_cmp_ne_u32_e64 s[0:1], 0, v9
	v_ashrrev_i32_e32 v27, 31, v26
	v_sub_u32_e32 v17, v9, v58
	v_min_u32_e32 v19, v21, v19
	s_and_b64 s[0:1], s[2:3], s[0:1]
	v_mov_b32_e32 v196, 0
	v_mov_b32_e32 v197, 0
	v_mov_b32_e32 v198, 0
	v_mov_b32_e32 v199, 0
	s_and_saveexec_b64 s[2:3], s[0:1]
	s_xor_b64 s[2:3], exec, s[2:3]
	s_cbranch_execz .LBB0_486
	v_cmp_gt_u32_e64 s[0:1], v19, v23
	v_mov_b32_e32 v198, 0
	v_mov_b32_e32 v196, 0
	v_mov_b32_e32 v197, 0
	s_and_saveexec_b64 s[4:5], s[0:1]
	s_cbranch_execz .LBB0_483
	v_add_u32_e32 v21, -1, v19
	s_movk_i32 s0, 0x1200
	v_mad_u64_u32 v[52:53], s[0:1], v21, s0, v[48:49]
	global_load_dwordx2 v[196:197], v[52:53], off
.LBB0_483:
	s_or_b64 exec, exec, s[4:5]
	v_cmp_gt_i32_e64 s[0:1], v17, v64
	v_mov_b32_e32 v199, 0
	s_and_saveexec_b64 s[4:5], s[0:1]
	s_cbranch_execz .LBB0_485
	s_movk_i32 s0, 0x1200
	v_mad_u64_u32 v[48:49], s[0:1], v64, s0, v[48:49]
	global_load_dwordx2 v[198:199], v[48:49], off
.LBB0_485:
	s_or_b64 exec, exec, s[4:5]
.LBB0_486:
	s_or_saveexec_b64 s[2:3], s[2:3]
	v_max_i32_e32 v64, 0, v17
	s_xor_b64 exec, exec, s[2:3]
	s_cbranch_execz .LBB0_498
	v_cmp_lt_i32_e64 s[0:1], v17, v19
	v_mov_b32_e32 v43, 0
	v_mov_b32_e32 v42, 0
	v_mov_b32_e32 v41, 0
	v_mov_b32_e32 v40, 0
	s_and_saveexec_b64 s[4:5], s[0:1]
	s_cbranch_execz .LBB0_497
	v_add_u32_e32 v21, 1, v64
	v_max_u32_e32 v54, v19, v21
	s_movk_i32 s0, 0x1200
	v_sub_u32_e32 v17, v54, v64
	v_mad_i64_i32 v[50:51], s[0:1], v63, s0, 0
	v_and_b32_e32 v23, 3, v17
	v_mov_b32_e32 v160, v161
	v_cmp_ne_u32_e64 s[0:1], 0, v23
	v_mul_hi_u32_u24_e32 v52, 0x1200, v9
	v_mul_u32_u24_e32 v53, 0x1200, v9
	v_add_u32_e32 v25, v64, v23
	v_mov_b64_e32 v[42:43], v[160:161]
	v_mov_b64_e32 v[40:41], v[160:161]
	v_mov_b32_e32 v17, v64
	s_and_saveexec_b64 s[6:7], s[0:1]
	s_cbranch_execz .LBB0_492
	s_movk_i32 s0, 0x1200
	v_mad_u64_u32 v[40:41], s[0:1], v64, s0, v[50:51]
	v_sub_co_u32_e64 v40, s[0:1], v40, v53
	v_mul_u32_u24_e32 v17, 0x1200, v23
	s_nop 0
	v_subb_co_u32_e64 v41, s[0:1], v41, v52, s[0:1]
	v_lshl_add_u64 v[48:49], v[10:11], 0, v[40:41]
	v_mov_b32_e32 v40, 0
	s_mov_b64 s[8:9], 0
	v_mov_b32_e32 v41, v40
	v_mov_b32_e32 v42, v40
	v_mov_b32_e32 v43, v40

.LBB0_507:
	s_or_b64 exec, exec, s[0:1]
	v_sub_u32_e32 v9, v17, v60
	v_cvt_f32_i32_e32 v9, v9
	s_waitcnt vmcnt(2)
	v_lshlrev_b32_e32 v200, 16, v196
	v_and_b32_e32 v201, 0xffff0000, v196
	v_lshlrev_b32_e32 v202, 16, v198
	v_and_b32_e32 v203, 0xffff0000, v198
	v_pk_add_f32 v[200:201], v[200:201], v[202:203] neg_lo:[0,1] neg_hi:[0,1]
	v_lshlrev_b32_e32 v198, 16, v199
	v_pk_add_f32 v[36:37], v[36:37], v[200:201]
	v_lshlrev_b32_e32 v200, 16, v197
	v_and_b32_e32 v201, 0xffff0000, v197
	v_and_b32_e32 v199, 0xffff0000, v199
	v_pk_add_f32 v[200:201], v[200:201], v[198:199] neg_lo:[0,1] neg_hi:[0,1]
	s_nop 0
	v_pk_add_f32 v[38:39], v[38:39], v[200:201]
	v_lshlrev_b32_e32 v34, 16, v32
	v_and_b32_e32 v35, 0xffff0000, v32
	s_add_i32 s14, s14, 1
	v_rcp_iflag_f32_e32 v30, v9
	v_lshl_add_u64 v[14:15], v[14:15], 0, s[34:35]
	s_cmp_eq_u32 s14, 8
	v_mov_b32_e32 v21, v17
	v_pk_fma_f32 v[34:35], v[30:31], v[36:37], v[34:35] op_sel_hi:[0,1,1] neg_lo:[0,0,1] neg_hi:[0,0,1]
	v_cvt_pk_bf16_f32 v32, v34, v35
	v_lshlrev_b32_e32 v34, 16, v33
	v_and_b32_e32 v35, 0xffff0000, v33
	v_pk_fma_f32 v[30:31], v[30:31], v[38:39], v[34:35] op_sel_hi:[0,1,1] neg_lo:[0,0,1] neg_hi:[0,0,1]
	v_cvt_pk_bf16_f32 v33, v30, v31
	v_lshlrev_b64 v[30:31], 11, v[160:161]
	v_lshl_add_u64 v[30:31], v[12:13], 0, v[30:31]
	v_mov_b32_e32 v42, v24
	v_mov_b32_e32 v43, v25
	v_mov_b32_e32 v40, v26
	v_mov_b32_e32 v41, v27
	v_mov_b32_e32 v34, v28
	v_mov_b32_e32 v35, v29
	global_store_dwordx2 v[30:31], v[32:33], off
	s_cbranch_scc1 .LBB0_530

.LBB0_510:
	s_movk_i32 s0, 0x3fff
	v_cmp_lt_u32_e64 s[40:41], s0, v160
	v_mov_b32_e32 v9, 0x7ff
	s_movk_i32 s0, 0x1200
	v_cndmask_b32_e64 v9, v9, v238, s[40:41]
	v_and_b32_e32 v9, v9, v160
	v_sub_u32_e32 v17, v160, v9
	v_mad_i64_i32 v[44:45], s[0:1], v17, s0, v[10:11]
	v_mul_u32_u24_e32 v17, 0x900, v9
	v_lshlrev_b32_e32 v32, 1, v17
	v_mov_b32_e32 v33, v161
	v_lshl_add_u64 v[32:33], v[44:45], 0, v[32:33]
	global_load_dwordx2 v[32:33], v[32:33], off
	v_mov_b32_e32 v17, 0x800
	s_cmp_lg_u32 s14, 0
	v_cndmask_b32_e64 v17, v17, v245, s[40:41]
	v_add_u32_e32 v23, v9, v55
	s_cselect_b64 s[4:5], -1, 0
	v_cmp_ne_u32_e64 s[0:1], 0, v9
	v_sub_u32_e32 v19, v9, v55
	v_min_u32_e32 v17, v23, v17
	s_and_b64 s[0:1], s[4:5], s[0:1]
	v_mov_b32_e32 v196, 0
	v_mov_b32_e32 v197, 0
	v_mov_b32_e32 v198, 0
	v_mov_b32_e32 v199, 0
	s_and_saveexec_b64 s[4:5], s[0:1]
	s_xor_b64 s[4:5], exec, s[4:5]
	s_cbranch_execz .LBB0_516
	v_cmp_gt_u32_e64 s[0:1], v17, v21
	v_mov_b32_e32 v198, 0
	v_mov_b32_e32 v196, 0
	v_mov_b32_e32 v197, 0
	s_and_saveexec_b64 s[6:7], s[0:1]
	s_cbranch_execz .LBB0_513
	v_add_u32_e32 v21, -1, v17
	s_movk_i32 s0, 0x1200
	v_mad_u64_u32 v[48:49], s[0:1], v21, s0, v[44:45]
	global_load_dwordx2 v[196:197], v[48:49], off
.LBB0_513:
	s_or_b64 exec, exec, s[6:7]
	v_cmp_gt_i32_e64 s[0:1], v19, v60
	v_mov_b32_e32 v199, 0
	s_and_saveexec_b64 s[6:7], s[0:1]
	s_cbranch_execz .LBB0_515
	s_movk_i32 s0, 0x1200
	v_mad_u64_u32 v[44:45], s[0:1], v60, s0, v[44:45]
	global_load_dwordx2 v[198:199], v[44:45], off
.LBB0_515:
	s_or_b64 exec, exec, s[6:7]
.LBB0_516:
	s_or_saveexec_b64 s[4:5], s[4:5]
	v_max_i32_e32 v60, 0, v19
	s_xor_b64 exec, exec, s[4:5]
	s_cbranch_execz .LBB0_528
	v_cmp_lt_i32_e64 s[0:1], v19, v17
	v_mov_b32_e32 v37, 0
	v_mov_b32_e32 v36, 0
	v_mov_b32_e32 v39, 0
	v_mov_b32_e32 v38, 0
	s_and_saveexec_b64 s[6:7], s[0:1]
	s_cbranch_execz .LBB0_527
	v_add_u32_e32 v21, 1, v60
	v_max_u32_e32 v46, v17, v21
	v_sub_u32_e32 v19, v46, v60
	v_and_b32_e32 v23, 3, v19
	v_mov_b32_e32 v36, v161
	v_mov_b32_e32 v37, v161
	v_cmp_ne_u32_e64 s[0:1], 0, v23
	v_add_u32_e32 v48, v60, v23
	v_mov_b64_e32 v[38:39], v[36:37]
	v_mov_b32_e32 v19, v60
	s_and_saveexec_b64 s[8:9], s[0:1]
	s_cbranch_execz .LBB0_522
	v_mul_u32_u24_e32 v36, 0x1200, v60
	v_mul_u32_u24_e32 v38, 0x1200, v9
	v_mul_hi_u32_u24_e32 v19, 0x1200, v60
	v_mul_hi_u32_u24_e32 v37, 0x1200, v9
	v_sub_co_u32_e64 v36, s[0:1], v36, v38
	v_mov_b32_e32 v38, 0
	s_nop 0
	v_subb_co_u32_e64 v37, s[0:1], v19, v37, s[0:1]
	v_lshl_add_u64 v[44:45], v[14:15], 0, v[36:37]
	v_mul_u32_u24_e32 v19, 0x1200, v23
	s_mov_b64 s[10:11], 0
	v_mov_b32_e32 v39, v38
	v_mov_b32_e32 v36, v38
	v_mov_b32_e32 v37, v38

.LBB0_533:
	s_or_b64 exec, exec, s[0:1]
	v_sub_u32_e32 v9, v17, v63
	v_cvt_f32_i32_e32 v9, v9
	s_waitcnt vmcnt(2)
	v_lshlrev_b32_e32 v200, 16, v196
	v_and_b32_e32 v201, 0xffff0000, v196
	v_lshlrev_b32_e32 v202, 16, v198
	v_and_b32_e32 v203, 0xffff0000, v198
	v_pk_add_f32 v[200:201], v[200:201], v[202:203] neg_lo:[0,1] neg_hi:[0,1]
	v_lshlrev_b32_e32 v198, 16, v199
	v_pk_add_f32 v[40:41], v[40:41], v[200:201]
	v_lshlrev_b32_e32 v200, 16, v197
	v_and_b32_e32 v201, 0xffff0000, v197
	v_and_b32_e32 v199, 0xffff0000, v199
	v_pk_add_f32 v[200:201], v[200:201], v[198:199] neg_lo:[0,1] neg_hi:[0,1]
	s_nop 0
	v_pk_add_f32 v[38:39], v[38:39], v[200:201]
	v_lshlrev_b32_e32 v36, 16, v34
	v_and_b32_e32 v37, 0xffff0000, v34
	s_add_i32 s14, s14, 1
	v_rcp_iflag_f32_e32 v32, v9
	v_lshlrev_b64 v[24:25], 11, v[24:25]
	v_lshl_add_u64 v[24:25], v[14:15], 0, v[24:25]
	v_add_u32_e32 v62, 1, v62
	v_pk_fma_f32 v[36:37], v[32:33], v[40:41], v[36:37] op_sel_hi:[0,1,1] neg_lo:[0,0,1] neg_hi:[0,0,1]
	v_cvt_pk_bf16_f32 v34, v36, v37
	v_lshlrev_b32_e32 v36, 16, v35
	v_and_b32_e32 v37, 0xffff0000, v35
	v_pk_fma_f32 v[32:33], v[32:33], v[38:39], v[36:37] op_sel_hi:[0,1,1] neg_lo:[0,0,1] neg_hi:[0,0,1]
	v_cvt_pk_bf16_f32 v35, v32, v33
	s_cmp_eq_u32 s14, 5
	v_mov_b32_e32 v21, v17
	v_mov_b32_e32 v44, v26
	v_mov_b32_e32 v45, v27
	v_mov_b32_e32 v42, v28
	v_mov_b32_e32 v43, v29
	v_mov_b32_e32 v36, v30
	v_mov_b32_e32 v37, v31
	global_store_dwordx2 v[24:25], v[34:35], off
	s_cbranch_scc1 .LBB0_556

.LBB0_536:
	s_movk_i32 s0, 0x3fff
	v_cmp_lt_i32_e64 s[40:41], s0, v24
	v_mov_b32_e32 v9, 0x7ff
	s_movk_i32 s0, 0x1200
	v_cndmask_b32_e64 v9, v9, v238, s[40:41]
	v_and_b32_e32 v9, v9, v24
	v_sub_u32_e32 v17, v24, v9
	v_mad_i64_i32 v[46:47], s[0:1], v17, s0, v[10:11]
	v_mul_u32_u24_e32 v17, 0x900, v9
	v_lshlrev_b32_e32 v160, 1, v17
	v_lshl_add_u64 v[34:35], v[46:47], 0, v[160:161]
	global_load_dwordx2 v[34:35], v[34:35], off
	v_mov_b32_e32 v17, 0x800
	s_cmp_lg_u32 s14, 0
	v_cndmask_b32_e64 v17, v17, v245, s[40:41]
	v_add_u32_e32 v23, v9, v57
	s_cselect_b64 s[4:5], -1, 0
	v_cmp_ne_u32_e64 s[0:1], 0, v9
	v_ashrrev_i32_e32 v25, 31, v24
	v_sub_u32_e32 v19, v9, v57
	v_min_u32_e32 v17, v23, v17
	s_and_b64 s[0:1], s[4:5], s[0:1]
	v_mov_b32_e32 v196, 0
	v_mov_b32_e32 v197, 0
	v_mov_b32_e32 v198, 0
	v_mov_b32_e32 v199, 0
	s_and_saveexec_b64 s[4:5], s[0:1]
	s_xor_b64 s[4:5], exec, s[4:5]
	s_cbranch_execz .LBB0_542
	v_cmp_gt_u32_e64 s[0:1], v17, v21
	v_mov_b32_e32 v198, 0
	v_mov_b32_e32 v196, 0
	v_mov_b32_e32 v197, 0
	s_and_saveexec_b64 s[6:7], s[0:1]
	s_cbranch_execz .LBB0_539
	v_add_u32_e32 v21, -1, v17
	s_movk_i32 s0, 0x1200
	v_mad_u64_u32 v[50:51], s[0:1], v21, s0, v[46:47]
	global_load_dwordx2 v[196:197], v[50:51], off
.LBB0_539:
	s_or_b64 exec, exec, s[6:7]
	v_cmp_gt_i32_e64 s[0:1], v19, v63
	v_mov_b32_e32 v199, 0
	s_and_saveexec_b64 s[6:7], s[0:1]
	s_cbranch_execz .LBB0_541
	s_movk_i32 s0, 0x1200
	v_mad_u64_u32 v[46:47], s[0:1], v63, s0, v[46:47]
	global_load_dwordx2 v[198:199], v[46:47], off
.LBB0_541:
	s_or_b64 exec, exec, s[6:7]
.LBB0_542:
	s_or_saveexec_b64 s[4:5], s[4:5]
	v_max_i32_e32 v63, 0, v19
	s_xor_b64 exec, exec, s[4:5]
	s_cbranch_execz .LBB0_554
	v_cmp_lt_i32_e64 s[0:1], v19, v17
	v_mov_b32_e32 v41, 0
	v_mov_b32_e32 v40, 0
	v_mov_b32_e32 v39, 0
	v_mov_b32_e32 v38, 0
	s_and_saveexec_b64 s[6:7], s[0:1]
	s_cbranch_execz .LBB0_553
	v_add_u32_e32 v21, 1, v63
	v_max_u32_e32 v53, v17, v21
	s_movk_i32 s0, 0x1200
	v_sub_u32_e32 v19, v53, v63
	v_mad_i64_i32 v[48:49], s[0:1], v62, s0, 0
	v_and_b32_e32 v23, 3, v19
	v_mov_b32_e32 v160, v161
	v_cmp_ne_u32_e64 s[0:1], 0, v23
	v_mul_hi_u32_u24_e32 v51, 0x1200, v9
	v_mul_u32_u24_e32 v52, 0x1200, v9
	v_add_u32_e32 v50, v63, v23
	v_mov_b64_e32 v[40:41], v[160:161]
	v_mov_b64_e32 v[38:39], v[160:161]
	v_mov_b32_e32 v19, v63
	s_and_saveexec_b64 s[8:9], s[0:1]
	s_cbranch_execz .LBB0_548
	s_movk_i32 s0, 0x1200
	v_mad_u64_u32 v[38:39], s[0:1], v63, s0, v[48:49]
	v_sub_co_u32_e64 v38, s[0:1], v38, v52
	v_mul_u32_u24_e32 v19, 0x1200, v23
	s_nop 0
	v_subb_co_u32_e64 v39, s[0:1], v39, v51, s[0:1]
	v_lshl_add_u64 v[46:47], v[10:11], 0, v[38:39]
	v_mov_b32_e32 v38, 0
	s_mov_b64 s[10:11], 0
	v_mov_b32_e32 v39, v38
	v_mov_b32_e32 v40, v38
	v_mov_b32_e32 v41, v38
